# v55 + the four v_pk_add_f32 of the d5_oproj MFMA loop split into scalar v_add_f32 pairs (packed-vs-scalar lever)
# speedup vs baseline: 1.0003x; 1.0003x over previous
.LBB0_1468:
	s_and_b32 s4, s7, 16
	s_mulk_i32 s4, 0x410
	s_add_i32 s9, s8, 1
	s_add_i32 s4, s4, 0
	v_lshlrev_b32_e32 v76, 1, v74
	s_add_i32 s96, s6, -1
	v_add3_u32 v93, s4, v91, v84
	v_add3_u32 v76, s4, v92, v76
	s_add_i32 s4, s8, 2
	s_min_i32 s4, s4, s96
	s_waitcnt vmcnt(4)
	ds_write_b128 v93, v[66:69]
	s_waitcnt vmcnt(4)
	ds_write_b128 v93, v[70:73] offset:512
	v_lshl_or_b32 v66, s4, 4, v1
	v_ashrrev_i32_e32 v67, 31, v66
	v_lshlrev_b64 v[66:67], 14, v[66:67]
	v_lshl_add_u64 v[94:95], v[86:87], 0, v[66:67]
	global_load_dwordx4 v[66:69], v[94:95], off
	global_load_dwordx4 v[70:73], v[94:95], off offset:512
	s_waitcnt lgkmcnt(0)
	s_barrier
	ds_read_b128 v[94:97], v76
	ds_read_b128 v[98:101], v76 offset:64
	ds_read_b128 v[102:105], v76 offset:128
	ds_read_b128 v[106:109], v76 offset:192
	s_waitcnt lgkmcnt(3)
	v_mfma_f32_16x16x32_bf16 v[94:97], v[2:5], v[94:97], 0
	v_add_u32_e32 v110, s7, v90
	v_ashrrev_i32_e32 v111, 31, v110
	s_add_i32 s7, s7, 16
	s_waitcnt lgkmcnt(2)
	v_mfma_f32_16x16x32_bf16 v[98:101], v[6:9], v[98:101], 0
	s_mov_b32 s8, s9
	s_cmp_ge_i32 s9, s6
	s_waitcnt lgkmcnt(1)
	v_mfma_f32_16x16x32_bf16 v[94:97], v[10:13], v[102:105], v[94:97]
	s_waitcnt lgkmcnt(0)
	v_mfma_f32_16x16x32_bf16 v[98:101], v[14:17], v[106:109], v[98:101]
	ds_read_b128 v[102:105], v76 offset:256
	ds_read_b128 v[106:109], v76 offset:320
	s_waitcnt lgkmcnt(1)
	v_mfma_f32_16x16x32_bf16 v[94:97], v[18:21], v[102:105], v[94:97]
	s_waitcnt lgkmcnt(0)
	v_mfma_f32_16x16x32_bf16 v[98:101], v[22:25], v[106:109], v[98:101]
	ds_read_b128 v[102:105], v76 offset:384
	ds_read_b128 v[106:109], v76 offset:448
	s_waitcnt lgkmcnt(1)
	v_mfma_f32_16x16x32_bf16 v[94:97], v[26:29], v[102:105], v[94:97]
	s_waitcnt lgkmcnt(0)
	v_mfma_f32_16x16x32_bf16 v[98:101], v[30:33], v[106:109], v[98:101]
	ds_read_b128 v[102:105], v76 offset:512
	ds_read_b128 v[106:109], v76 offset:576
	s_waitcnt lgkmcnt(1)
	v_mfma_f32_16x16x32_bf16 v[94:97], v[34:37], v[102:105], v[94:97]
	s_waitcnt lgkmcnt(0)
	v_mfma_f32_16x16x32_bf16 v[98:101], v[38:41], v[106:109], v[98:101]
	ds_read_b128 v[102:105], v76 offset:640
	ds_read_b128 v[106:109], v76 offset:704
	s_waitcnt lgkmcnt(1)
	v_mfma_f32_16x16x32_bf16 v[94:97], v[42:45], v[102:105], v[94:97]
	s_waitcnt lgkmcnt(0)
	v_mfma_f32_16x16x32_bf16 v[98:101], v[46:49], v[106:109], v[98:101]
	ds_read_b128 v[102:105], v76 offset:768
	ds_read_b128 v[106:109], v76 offset:832
	s_waitcnt lgkmcnt(1)
	v_mfma_f32_16x16x32_bf16 v[94:97], v[50:53], v[102:105], v[94:97]
	v_lshlrev_b64 v[102:103], 12, v[110:111]
	v_lshl_add_u64 v[110:111], v[88:89], 0, v[102:103]
	s_waitcnt lgkmcnt(0)
	v_mfma_f32_16x16x32_bf16 v[98:101], v[54:57], v[106:109], v[98:101]
	ds_read_b128 v[102:105], v76 offset:896
	ds_read_b128 v[106:109], v76 offset:960
	s_waitcnt lgkmcnt(1)
	v_mfma_f32_16x16x32_bf16 v[94:97], v[58:61], v[102:105], v[94:97]
	s_waitcnt lgkmcnt(0)
	v_mfma_f32_16x16x32_bf16 v[98:101], v[62:65], v[106:109], v[98:101]
	s_nop 7
	v_add_f32_e32 v96, v96, v100
	v_add_f32_e32 v97, v97, v101
	v_add_f32_e32 v94, v94, v98
	v_add_f32_e32 v95, v95, v99
	s_nop 0
	v_cvt_pk_bf16_f32 v94, v94, v95
	v_cvt_pk_bf16_f32 v95, v96, v97
	global_store_dwordx2 v[110:111], v[94:95], off
	s_cbranch_scc1 .LBB0_1465
.Lop_b:
	s_and_b32 s4, s7, 16
	s_mulk_i32 s4, 0x410
	s_add_i32 s9, s8, 1
	s_add_i32 s4, s4, 0
	v_lshlrev_b32_e32 v76, 1, v74
	s_add_i32 s96, s6, -1
	v_add3_u32 v93, s4, v91, v84
	v_add3_u32 v76, s4, v92, v76
	s_add_i32 s4, s8, 2
	s_min_i32 s4, s4, s96
	s_waitcnt vmcnt(4)
	ds_write_b128 v93, v[112:115]
	s_waitcnt vmcnt(4)
	ds_write_b128 v93, v[116:119] offset:512
	v_lshl_or_b32 v112, s4, 4, v1
	v_ashrrev_i32_e32 v113, 31, v112
	v_lshlrev_b64 v[112:113], 14, v[112:113]
	v_lshl_add_u64 v[94:95], v[86:87], 0, v[112:113]
	global_load_dwordx4 v[112:115], v[94:95], off
	global_load_dwordx4 v[116:119], v[94:95], off offset:512
	s_waitcnt lgkmcnt(0)
	s_barrier
	ds_read_b128 v[94:97], v76
	ds_read_b128 v[98:101], v76 offset:64
	ds_read_b128 v[102:105], v76 offset:128
	ds_read_b128 v[106:109], v76 offset:192
	s_waitcnt lgkmcnt(3)
	v_mfma_f32_16x16x32_bf16 v[94:97], v[2:5], v[94:97], 0
	v_add_u32_e32 v110, s7, v90
	v_ashrrev_i32_e32 v111, 31, v110
	s_add_i32 s7, s7, 16
	s_waitcnt lgkmcnt(2)
	v_mfma_f32_16x16x32_bf16 v[98:101], v[6:9], v[98:101], 0
	s_mov_b32 s8, s9
	s_cmp_ge_i32 s9, s6
	s_waitcnt lgkmcnt(1)
	v_mfma_f32_16x16x32_bf16 v[94:97], v[10:13], v[102:105], v[94:97]
	s_waitcnt lgkmcnt(0)
	v_mfma_f32_16x16x32_bf16 v[98:101], v[14:17], v[106:109], v[98:101]
	ds_read_b128 v[102:105], v76 offset:256
	ds_read_b128 v[106:109], v76 offset:320
	s_waitcnt lgkmcnt(1)
	v_mfma_f32_16x16x32_bf16 v[94:97], v[18:21], v[102:105], v[94:97]
	s_waitcnt lgkmcnt(0)
	v_mfma_f32_16x16x32_bf16 v[98:101], v[22:25], v[106:109], v[98:101]
	ds_read_b128 v[102:105], v76 offset:384
	ds_read_b128 v[106:109], v76 offset:448
	s_waitcnt lgkmcnt(1)
	v_mfma_f32_16x16x32_bf16 v[94:97], v[26:29], v[102:105], v[94:97]
	s_waitcnt lgkmcnt(0)
	v_mfma_f32_16x16x32_bf16 v[98:101], v[30:33], v[106:109], v[98:101]
	ds_read_b128 v[102:105], v76 offset:512
	ds_read_b128 v[106:109], v76 offset:576
	s_waitcnt lgkmcnt(1)
	v_mfma_f32_16x16x32_bf16 v[94:97], v[34:37], v[102:105], v[94:97]
	s_waitcnt lgkmcnt(0)
	v_mfma_f32_16x16x32_bf16 v[98:101], v[38:41], v[106:109], v[98:101]
	ds_read_b128 v[102:105], v76 offset:640
	ds_read_b128 v[106:109], v76 offset:704
	s_waitcnt lgkmcnt(1)
	v_mfma_f32_16x16x32_bf16 v[94:97], v[42:45], v[102:105], v[94:97]
	s_waitcnt lgkmcnt(0)
	v_mfma_f32_16x16x32_bf16 v[98:101], v[46:49], v[106:109], v[98:101]
	ds_read_b128 v[102:105], v76 offset:768
	ds_read_b128 v[106:109], v76 offset:832
	s_waitcnt lgkmcnt(1)
	v_mfma_f32_16x16x32_bf16 v[94:97], v[50:53], v[102:105], v[94:97]
	v_lshlrev_b64 v[102:103], 12, v[110:111]
	v_lshl_add_u64 v[110:111], v[88:89], 0, v[102:103]
	s_waitcnt lgkmcnt(0)
	v_mfma_f32_16x16x32_bf16 v[98:101], v[54:57], v[106:109], v[98:101]
	ds_read_b128 v[102:105], v76 offset:896
	ds_read_b128 v[106:109], v76 offset:960
	s_waitcnt lgkmcnt(1)
	v_mfma_f32_16x16x32_bf16 v[94:97], v[58:61], v[102:105], v[94:97]
	s_waitcnt lgkmcnt(0)
	v_mfma_f32_16x16x32_bf16 v[98:101], v[62:65], v[106:109], v[98:101]
	s_nop 7
	v_add_f32_e32 v96, v96, v100
	v_add_f32_e32 v97, v97, v101
	v_add_f32_e32 v94, v94, v98
	v_add_f32_e32 v95, v95, v99
	s_nop 0
	v_cvt_pk_bf16_f32 v94, v94, v95
	v_cvt_pk_bf16_f32 v95, v96, v97
	global_store_dwordx2 v[110:111], v[94:95], off
	s_cbranch_scc0 .LBB0_1468
	s_branch .LBB0_1465
